# speedup vs baseline: 1.0092x; 1.0092x over previous
; #define SBAR() __builtin_amdgcn_sched_barrier(0)
; __device__ __forceinline__ void partialSM(f32x16& p0, f32x16& p1, float& m_reg, float& mn, float& alpha) {
;   constexpr float C = ASCALE * 1.4426950408889634f;
;   float pmax = p0[0];
; #pragma unroll
;   for (int r = 1; r < 16; ++r) pmax = fmaxf(pmax, p0[r]);
; #pragma unroll
;   for (int r = 0; r < 16; ++r) pmax = fmaxf(pmax, p1[r]);
;   { auto rr = __builtin_amdgcn_permlane32_swap(__float_as_uint(pmax), __float_as_uint(pmax), false, false);
;     pmax = fmaxf(__uint_as_float(rr[0]), __uint_as_float(rr[1])); }
;   if (__builtin_expect(__all(pmax - m_reg <= ATHR / ASCALE), 1)) { mn = m_reg; alpha = 1.f; }
;   else { mn = fmaxf(m_reg, pmax); alpha = __builtin_amdgcn_exp2f((m_reg - mn) * C); m_reg = mn; }
; template <int D0> __device__ __forceinline__ void pv_one(f32x16& od, int vb, bf16x8 pa0, bf16x8 pa1, bf16x8 pa2, bf16x8 pa3) {
;   const s16x4 l0 = tr_read<v_rd_off(D0, 0, 0)>(vb), h0 = tr_read<v_rd_off(D0, 0, 1)>(vb), l1 = tr_read<v_rd_off(D0, 1, 0)>(vb), h1 = tr_read<v_rd_off(D0, 1, 1)>(vb);
;   const s16x4 l2 = tr_read<v_rd_off(D0, 2, 0)>(vb), h2 = tr_read<v_rd_off(D0, 2, 1)>(vb), l3 = tr_read<v_rd_off(D0, 3, 0)>(vb), h3 = tr_read<v_rd_off(D0, 3, 1)>(vb);
;   asm volatile("s_waitcnt lgkmcnt(0)" ::: "memory"); SBAR();
;     ...
;   od = __builtin_amdgcn_mfma_f32_32x32x16_bf16(pa0, PK(l0, h0), od, 0, 0, 0);
;   od = __builtin_amdgcn_mfma_f32_32x32x16_bf16(pa1, PK(l1, h1), od, 0, 0, 0);
;   od = __builtin_amdgcn_mfma_f32_32x32x16_bf16(pa2, PK(l2, h2), od, 0, 0, 0);
;   od = __builtin_amdgcn_mfma_f32_32x32x16_bf16(pa3, PK(l3, h3), od, 0, 0, 0);
;     ...
; }
; __device__ __forceinline__ void pv_d0(f32x16* o, int vb, bf16x8 pa0, bf16x8 pa1, bf16x8 pa2, bf16x8 pa3) {
;   pv_one<0>(o[0], vb, pa0, pa1, pa2, pa3); pv_one<1>(o[1], vb, pa0, pa1, pa2, pa3); pv_one<2>(o[2], vb, pa0, pa1, pa2, pa3); pv_one<3>(o[3], vb, pa0, pa1, pa2, pa3);
; }
; __device__ __forceinline__ void mask_last(f32x16& p0, f32x16& p1) {
; #pragma unroll
;   for (int r = 8; r < 16; ++r) p0[r] = -1e30f;
; #pragma unroll
;   for (int r = 0; r < 16; ++r) p1[r] = -1e30f;
; }
.LBB0_266:
	s_and_b64 vcc, exec, s[40:41]
	s_cbranch_vccz .Latt_nomask
	v_mov_b32_e32 v74, v246
	v_mov_b32_e32 v75, v246
	v_mov_b32_e32 v76, v246
	v_mov_b32_e32 v77, v246
	v_mov_b32_e32 v78, v246
	v_mov_b32_e32 v79, v246
	v_mov_b32_e32 v80, v246
	v_mov_b32_e32 v81, v246
	v_mov_b32_e32 v82, v246
	v_mov_b32_e32 v83, v246
	v_mov_b32_e32 v84, v246
	v_mov_b32_e32 v85, v246
	v_mov_b32_e32 v86, v246
	v_mov_b32_e32 v87, v246
	v_mov_b32_e32 v88, v246
	v_mov_b32_e32 v89, v246
	v_mov_b32_e32 v90, v246
	v_mov_b32_e32 v91, v246
	v_mov_b32_e32 v92, v246
	v_mov_b32_e32 v93, v246
	v_mov_b32_e32 v94, v246
	v_mov_b32_e32 v95, v246
	v_mov_b32_e32 v96, v246
	v_mov_b32_e32 v97, v246
.Latt_nomask:
	v_add_u32_e32 v198, s9, v178
	ds_read_b64_tr_b16 v[212:213], v198 offset:0
	ds_read_b64_tr_b16 v[214:215], v198 offset:0x800
	ds_read_b64_tr_b16 v[216:217], v198 offset:0x1000
	ds_read_b64_tr_b16 v[218:219], v198 offset:0x1800
	ds_read_b64_tr_b16 v[220:221], v198 offset:0x2000
	ds_read_b64_tr_b16 v[222:223], v198 offset:0x2800
	ds_read_b64_tr_b16 v[224:225], v198 offset:0x3000
	ds_read_b64_tr_b16 v[226:227], v198 offset:0x3800
	s_waitcnt lgkmcnt(6)
	s_nop 0
	v_mfma_f32_32x32x16_bf16 v[2:17], v[146:149], v[212:215], v[2:17]
	ds_read_b64_tr_b16 v[212:213], v198 offset:0x200
	ds_read_b64_tr_b16 v[214:215], v198 offset:0xa00
	s_waitcnt lgkmcnt(6)
	v_mfma_f32_32x32x16_bf16 v[2:17], v[150:153], v[216:219], v[2:17]
	ds_read_b64_tr_b16 v[216:217], v198 offset:0x1200
	ds_read_b64_tr_b16 v[218:219], v198 offset:0x1a00
	s_waitcnt lgkmcnt(6)
	v_mfma_f32_32x32x16_bf16 v[2:17], v[154:157], v[220:223], v[2:17]
	ds_read_b64_tr_b16 v[220:221], v198 offset:0x2200
	ds_read_b64_tr_b16 v[222:223], v198 offset:0x2a00
	s_waitcnt lgkmcnt(6)
	v_mfma_f32_32x32x16_bf16 v[2:17], v[158:161], v[224:227], v[2:17]
	ds_read_b64_tr_b16 v[224:225], v198 offset:0x3200
	ds_read_b64_tr_b16 v[226:227], v198 offset:0x3a00
	s_waitcnt lgkmcnt(6)
	v_mfma_f32_32x32x16_bf16 v[50:65], v[146:149], v[212:215], v[50:65]
	ds_read_b64_tr_b16 v[212:213], v198 offset:0x400
	ds_read_b64_tr_b16 v[214:215], v198 offset:0xc00
	s_waitcnt lgkmcnt(6)
	v_mfma_f32_32x32x16_bf16 v[50:65], v[150:153], v[216:219], v[50:65]
	ds_read_b64_tr_b16 v[216:217], v198 offset:0x1400
	ds_read_b64_tr_b16 v[218:219], v198 offset:0x1c00
	s_waitcnt lgkmcnt(6)
	v_mfma_f32_32x32x16_bf16 v[50:65], v[154:157], v[220:223], v[50:65]
	ds_read_b64_tr_b16 v[220:221], v198 offset:0x2400
	ds_read_b64_tr_b16 v[222:223], v198 offset:0x2c00
	s_waitcnt lgkmcnt(6)
	v_mfma_f32_32x32x16_bf16 v[50:65], v[158:161], v[224:227], v[50:65]
	ds_read_b64_tr_b16 v[224:225], v198 offset:0x3400
	ds_read_b64_tr_b16 v[226:227], v198 offset:0x3c00
	s_waitcnt lgkmcnt(6)
	v_mfma_f32_32x32x16_bf16 v[34:49], v[146:149], v[212:215], v[34:49]
	ds_read_b64_tr_b16 v[212:213], v198 offset:0x600
	ds_read_b64_tr_b16 v[214:215], v198 offset:0xe00
	s_waitcnt lgkmcnt(6)
	v_mfma_f32_32x32x16_bf16 v[34:49], v[150:153], v[216:219], v[34:49]
	ds_read_b64_tr_b16 v[216:217], v198 offset:0x1600
	ds_read_b64_tr_b16 v[218:219], v198 offset:0x1e00
	s_waitcnt lgkmcnt(6)
	v_mfma_f32_32x32x16_bf16 v[34:49], v[154:157], v[220:223], v[34:49]
	ds_read_b64_tr_b16 v[220:221], v198 offset:0x2600
	ds_read_b64_tr_b16 v[222:223], v198 offset:0x2e00
	s_waitcnt lgkmcnt(6)
	v_mfma_f32_32x32x16_bf16 v[34:49], v[158:161], v[224:227], v[34:49]
	ds_read_b64_tr_b16 v[224:225], v198 offset:0x3600
	ds_read_b64_tr_b16 v[226:227], v198 offset:0x3e00
	s_waitcnt lgkmcnt(6)
	v_mfma_f32_32x32x16_bf16 v[18:33], v[146:149], v[212:215], v[18:33]
	v_max_f32_e32 v230, v67, v67
	v_max_f32_e32 v231, v66, v66
	v_max_f32_e32 v230, v231, v230
	v_max3_f32 v230, v230, v68, v69
	v_max3_f32 v230, v230, v70, v71
	v_max3_f32 v230, v230, v72, v73
	v_max3_f32 v230, v230, v74, v75
	v_max3_f32 v230, v230, v76, v77
	v_max3_f32 v230, v230, v78, v79
	s_waitcnt lgkmcnt(4)
	v_mfma_f32_32x32x16_bf16 v[18:33], v[150:153], v[216:219], v[18:33]
	v_max3_f32 v230, v230, v80, v81
	v_max3_f32 v230, v230, v82, v83
	v_max3_f32 v230, v230, v84, v85
	v_max3_f32 v230, v230, v86, v87
	v_max3_f32 v230, v230, v88, v89
	v_max3_f32 v230, v230, v90, v91
	v_max3_f32 v230, v230, v92, v93
	v_max3_f32 v230, v230, v94, v95
	s_waitcnt lgkmcnt(2)
	v_mfma_f32_32x32x16_bf16 v[18:33], v[154:157], v[220:223], v[18:33]
	v_max3_f32 v230, v230, v96, v97
	v_mov_b32_e32 v231, v230
	s_nop 1
	v_permlane32_swap_b32_e32 v230, v231
	v_max_f32_e32 v231, v231, v231
	v_max_f32_e32 v230, v230, v230
	v_max_f32_e32 v230, v230, v231
	v_sub_f32_e32 v231, v230, v209
	v_cmp_ge_f32_e32 vcc, s25, v231
	v_max_f32_e32 v231, v209, v209
	v_max_f32_e32 v231, v231, v230
	s_waitcnt lgkmcnt(0)
	v_mfma_f32_32x32x16_bf16 v[18:33], v[158:161], v[224:227], v[18:33]
	v_sub_f32_e32 v230, v209, v231
	v_mul_f32_e32 v230, 0x3e0293ee, v230
	s_cmp_eq_u64 vcc, exec
	v_exp_f32_e32 v230, v230
	s_cselect_b64 s[40:41], -1, 0
	s_add_i32 s0, s8, 0
	v_add_u32_e32 v232, s0, v176
	s_waitcnt vmcnt(0)
	s_waitcnt vmcnt(3)
	ds_write_b128 v232, v[130:133]
	v_add_u32_e32 v232, s0, v177
	v_cndmask_b32_e64 v230, v230, 1.0, s[40:41]
	s_waitcnt vmcnt(2)
	ds_write_b128 v232, v[134:137]
	v_add_u32_e32 v232, s0, v179
	s_waitcnt vmcnt(1)
	ds_write_b128 v232, v[138:141] offset:49152
	v_add_u32_e32 v232, s0, v180
	v_cmp_gt_f32_e32 vcc, 1.0, v230
	s_waitcnt vmcnt(0)
	ds_write_b128 v232, v[142:145] offset:49152
	s_cbranch_vccz .LBB0_270
; __device__ __forceinline__ void partialSM(f32x16& p0, f32x16& p1, float& m_reg, float& mn, float& alpha) {
;     ...
;   float mnC = -mn * C;
; #pragma unroll
;   for (int r = 0; r < 16; ++r) p0[r] = fmaf(p0[r], C, mnC);
; #pragma unroll
;   for (int r = 0; r < 16; ++r) p1[r] = fmaf(p1[r], C, mnC);
; #pragma unroll
;   for (int r = 0; r < 16; ++r) p0[r] = __builtin_amdgcn_exp2f(p0[r]);
	s_and_saveexec_b64 s[0:1], s[38:39]
	ds_write_b32 v190, v230 offset:128
	s_or_b64 exec, exec, s[0:1]
	s_waitcnt lgkmcnt(0)
	v_add_u32_e32 v236, v173, v181
	ds_read_b128 v[232:235], v236 offset:224
	ds_read_b128 v[130:133], v236 offset:192
	ds_read_b128 v[134:137], v236 offset:160
	ds_read_b128 v[138:141], v236 offset:128
	s_waitcnt lgkmcnt(3)
	v_pk_mul_f32 v[14:15], v[14:15], v[232:233]
	s_waitcnt lgkmcnt(2)
	v_pk_mul_f32 v[10:11], v[10:11], v[130:131]
	s_waitcnt lgkmcnt(1)
	v_pk_mul_f32 v[6:7], v[6:7], v[134:135]
	v_pk_mul_f32 v[16:17], v[16:17], v[234:235]
	v_pk_mul_f32 v[12:13], v[12:13], v[132:133]
	v_pk_mul_f32 v[8:9], v[8:9], v[136:137]
	s_waitcnt lgkmcnt(0)
	v_pk_mul_f32 v[4:5], v[4:5], v[140:141]
	v_pk_mul_f32 v[2:3], v[2:3], v[138:139]
	v_pk_mul_f32 v[62:63], v[62:63], v[232:233]
	v_pk_mul_f32 v[58:59], v[58:59], v[130:131]
	v_pk_mul_f32 v[54:55], v[54:55], v[134:135]
	v_pk_mul_f32 v[64:65], v[64:65], v[234:235]
	v_pk_mul_f32 v[60:61], v[60:61], v[132:133]
	v_pk_mul_f32 v[56:57], v[56:57], v[136:137]
	v_pk_mul_f32 v[52:53], v[52:53], v[140:141]
	v_pk_mul_f32 v[50:51], v[50:51], v[138:139]
	v_pk_mul_f32 v[46:47], v[46:47], v[232:233]
	v_pk_mul_f32 v[42:43], v[42:43], v[130:131]
	v_pk_mul_f32 v[38:39], v[38:39], v[134:135]
	v_pk_mul_f32 v[48:49], v[48:49], v[234:235]
	v_pk_mul_f32 v[44:45], v[44:45], v[132:133]
	v_pk_mul_f32 v[40:41], v[40:41], v[136:137]
	v_pk_mul_f32 v[36:37], v[36:37], v[140:141]
	v_pk_mul_f32 v[34:35], v[34:35], v[138:139]
	v_pk_mul_f32 v[30:31], v[30:31], v[232:233]
	v_pk_mul_f32 v[26:27], v[26:27], v[130:131]
	v_pk_mul_f32 v[22:23], v[22:23], v[134:135]
	v_pk_mul_f32 v[32:33], v[32:33], v[234:235]
	v_pk_mul_f32 v[28:29], v[28:29], v[132:133]
	v_pk_mul_f32 v[24:25], v[24:25], v[136:137]
	v_pk_mul_f32 v[20:21], v[20:21], v[140:141]
	v_pk_mul_f32 v[18:19], v[18:19], v[138:139]
.LBB0_270:
	v_cndmask_b32_e64 v150, v231, v209, s[40:41]
	v_mul_f32_e32 v232, 0xbe0293ee, v150
	v_mov_b32_e32 v158, v232
	v_fmamk_f32 v66, v66, 0x3e0293ee, v232
	v_fmamk_f32 v67, v67, 0x3e0293ee, v232
	v_fmamk_f32 v68, v68, 0x3e0293ee, v232
	v_fmamk_f32 v69, v69, 0x3e0293ee, v232
	v_fmamk_f32 v70, v70, 0x3e0293ee, v232
	v_fmamk_f32 v71, v71, 0x3e0293ee, v232
	v_fmamk_f32 v72, v72, 0x3e0293ee, v232
	v_fmamk_f32 v73, v73, 0x3e0293ee, v232
	v_fmamk_f32 v231, v74, 0x3e0293ee, v232
	v_fmamk_f32 v233, v75, 0x3e0293ee, v232
	v_fmamk_f32 v234, v76, 0x3e0293ee, v232
	v_fmamk_f32 v235, v77, 0x3e0293ee, v232
	v_fmamk_f32 v236, v78, 0x3e0293ee, v232
	v_fmamk_f32 v237, v79, 0x3e0293ee, v232
	v_fmamk_f32 v156, v80, 0x3e0293ee, v232
	v_fmac_f32_e32 v158, 0x3e0293ee, v81
	v_exp_f32_e32 v146, v66
	v_exp_f32_e32 v147, v67
	v_exp_f32_e32 v148, v68
	v_exp_f32_e32 v159, v69
	v_exp_f32_e32 v160, v70
	v_exp_f32_e32 v209, v71
	v_exp_f32_e32 v149, v72
	v_exp_f32_e32 v161, v73
	v_exp_f32_e32 v151, v231
	v_exp_f32_e32 v153, v233
	v_exp_f32_e32 v154, v234
	v_exp_f32_e32 v157, v235
	v_exp_f32_e32 v152, v236
	v_exp_f32_e32 v155, v237
	v_exp_f32_e32 v156, v156
	v_exp_f32_e32 v158, v158
	v_add_f32_e32 v66, v193, v195
	s_add_u32 s90, s90, 0x80
	v_fmac_f32_e32 v66, v192, v0
	v_add_f32_e32 v0, v210, v211
	s_addc_u32 s91, s91, 0
	v_pk_fma_f32 v[144:145], v[82:83], s[36:37], v[232:233] op_sel_hi:[1,0,0]
	v_pk_fma_f32 v[142:143], v[84:85], s[36:37], v[232:233] op_sel_hi:[1,0,0]
	v_pk_fma_f32 v[140:141], v[86:87], s[36:37], v[232:233] op_sel_hi:[1,0,0]
	v_pk_fma_f32 v[138:139], v[88:89], s[36:37], v[232:233] op_sel_hi:[1,0,0]
	v_pk_fma_f32 v[136:137], v[90:91], s[36:37], v[232:233] op_sel_hi:[1,0,0]
	v_pk_fma_f32 v[134:135], v[92:93], s[36:37], v[232:233] op_sel_hi:[1,0,0]
	v_pk_fma_f32 v[132:133], v[94:95], s[36:37], v[232:233] op_sel_hi:[1,0,0]
	v_pk_fma_f32 v[130:131], v[96:97], s[36:37], v[232:233] op_sel_hi:[1,0,0]
	v_fmac_f32_e32 v0, v66, v196
	s_cmpk_gt_u32 s4, 0xfd
	s_waitcnt lgkmcnt(0)
	s_barrier
	s_cbranch_scc1 .LBB0_272
	v_mov_b32_e32 v192, v230
	s_branch .LBB0_260
; __device__ __forceinline__ void finishSM(f32x16& p0, f32x16& p1, float alpha, float& l_reg, bf16x8& pa0, bf16x8& pa1, bf16x8& pa2, bf16x8& pa3) {
; #pragma unroll
;   for (int r = 0; r < 16; ++r) p1[r] = __builtin_amdgcn_exp2f(p1[r]);
;   float ps = 0;
; #pragma unroll
;   for (int r = 0; r < 16; ++r) ps += p0[r];
; #pragma unroll
;   for (int r = 0; r < 16; ++r) ps += p1[r];
;   { auto rr = __builtin_amdgcn_permlane32_swap(__float_as_uint(ps), __float_as_uint(ps), false, false);
;     ps = __uint_as_float(rr[0]) + __uint_as_float(rr[1]); }
;   l_reg = l_reg * alpha + ps;
;     ...
;   PK4(p0, 0, pa0); PK4(p0, 8, pa1); PK4(p1, 0, pa2); PK4(p1, 8, pa3);
;     ...
; }
; __device__ __forceinline__ void qkt(f32x16& p0, f32x16& p1, const bf16_t* Ks, const bf16x8* qr, int r32, int hi) {
;   p0 = f32x16{}; p1 = f32x16{};
; #pragma unroll
;   for (int d0 = 0; d0 < 8; ++d0) { int cb = (d0 * 16 + hi * 8) * 2;
;     bf16x8 b0 = *reinterpret_cast<const bf16x8*>((const char*)Ks + KSWZ(r32, cb));
;     bf16x8 b1 = *reinterpret_cast<const bf16x8*>((const char*)Ks + KSWZ(32 + r32, cb));
;     p0 = __builtin_amdgcn_mfma_f32_32x32x16_bf16(b0, qr[d0], p0, 0, 0, 0);
;     p1 = __builtin_amdgcn_mfma_f32_32x32x16_bf16(b1, qr[d0], p1, 0, 0, 0); }
; }
; __device__ __forceinline__ int v_st(int k, int c) { const int kk = (k & ~0xC) | ((k & 4) << 1) | ((k & 8) >> 1); return ((kk >> 3) * 4 + (c >> 5)) * 512 + ((kk & 7) * 32 + (c & 31)) * 2; }
; __device__ __forceinline__ int v_rd_base(int lane) { return ((lane & 3) << 3) | (((lane >> 2) & 3) << 6) | (((lane >> 4) & 1) << 5) | (((lane >> 5) & 1) << 8); }
; template <int OFF> __device__ __forceinline__ s16x4 tr_read(int vb) {
;   s16x4 r; asm volatile("ds_read_b64_tr_b16 %0, %1 offset:%2" : "=&v"(r) : "v"(vb), "i"(OFF) : "memory"); return r;
; }
; template <int D0> __device__ __forceinline__ void pv_one(f32x16& od, int vb, bf16x8 pa0, bf16x8 pa1, bf16x8 pa2, bf16x8 pa3) {
;   const s16x4 l0 = tr_read<v_rd_off(D0, 0, 0)>(vb), h0 = tr_read<v_rd_off(D0, 0, 1)>(vb), l1 = tr_read<v_rd_off(D0, 1, 0)>(vb), h1 = tr_read<v_rd_off(D0, 1, 1)>(vb);
;   const s16x4 l2 = tr_read<v_rd_off(D0, 2, 0)>(vb), h2 = tr_read<v_rd_off(D0, 2, 1)>(vb), l3 = tr_read<v_rd_off(D0, 3, 0)>(vb), h3 = tr_read<v_rd_off(D0, 3, 1)>(vb);
;   asm volatile("s_waitcnt lgkmcnt(0)" ::: "memory"); SBAR();
;     ...
;   od = __builtin_amdgcn_mfma_f32_32x32x16_bf16(pa0, PK(l0, h0), od, 0, 0, 0);
.LBB0_272:
	v_add_f32_e32 v66, 0, v146
	v_add_f32_e32 v66, v147, v66
	v_add_f32_e32 v66, v148, v66
	v_add_f32_e32 v66, v159, v66
	v_add_f32_e32 v66, v160, v66
	v_add_f32_e32 v66, v209, v66
	v_add_f32_e32 v66, v149, v66
	v_add_f32_e32 v66, v161, v66
	v_add_f32_e32 v66, v151, v66
	v_add_f32_e32 v66, v153, v66
	v_add_f32_e32 v66, v154, v66
	v_add_f32_e32 v66, v157, v66
	v_exp_f32_e32 v76, v144
	v_add_f32_e32 v66, v152, v66
	v_exp_f32_e32 v77, v145
	v_add_f32_e32 v66, v155, v66
	v_exp_f32_e32 v78, v142
	v_add_f32_e32 v66, v156, v66
	v_exp_f32_e32 v79, v143
	v_add_f32_e32 v66, v158, v66
	v_exp_f32_e32 v80, v140
	v_add_f32_e32 v66, v76, v66
	v_exp_f32_e32 v81, v141
	v_add_f32_e32 v66, v77, v66
	v_exp_f32_e32 v82, v138
	v_add_f32_e32 v66, v78, v66
	v_exp_f32_e32 v83, v139
	v_add_f32_e32 v66, v79, v66
	v_exp_f32_e32 v84, v136
	v_add_f32_e32 v66, v80, v66
	v_exp_f32_e32 v85, v137
	v_add_f32_e32 v66, v81, v66
	v_exp_f32_e32 v86, v134
	v_add_f32_e32 v66, v82, v66
	v_exp_f32_e32 v87, v135
	v_add_f32_e32 v66, v83, v66
	v_exp_f32_e32 v88, v132
	v_add_f32_e32 v66, v84, v66
	v_exp_f32_e32 v89, v133
	v_add_f32_e32 v66, v85, v66
	v_exp_f32_e32 v91, v130
	v_add_f32_e32 v66, v86, v66
	v_exp_f32_e32 v92, v131
	v_add_f32_e32 v66, v87, v66
	v_add_f32_e32 v66, v88, v66
	v_add_f32_e32 v66, v89, v66
	v_add_f32_e32 v66, v91, v66
	v_add_f32_e32 v66, v92, v66
	v_mov_b32_e32 v67, v66
	s_nop 1
	v_permlane32_swap_b32_e32 v66, v67
	v_cvt_pk_bf16_f32 v68, v146, v147
	v_cvt_pk_bf16_f32 v69, v148, v159
	v_cvt_pk_bf16_f32 v70, v160, v209
	v_cvt_pk_bf16_f32 v71, v149, v161
	v_cvt_pk_bf16_f32 v72, v151, v153
	v_cvt_pk_bf16_f32 v73, v154, v157
	v_cvt_pk_bf16_f32 v74, v152, v155
	v_cvt_pk_bf16_f32 v75, v156, v158
	v_cvt_pk_bf16_f32 v76, v76, v77
	v_cvt_pk_bf16_f32 v77, v78, v79
	v_cvt_pk_bf16_f32 v78, v80, v81
	v_cvt_pk_bf16_f32 v79, v82, v83
	v_cvt_pk_bf16_f32 v80, v84, v85
	v_cvt_pk_bf16_f32 v81, v86, v87
	v_cvt_pk_bf16_f32 v82, v88, v89
	v_cvt_pk_bf16_f32 v83, v91, v92
	v_permlane32_swap_b32_e32 v68, v70
	v_permlane32_swap_b32_e32 v69, v71
	v_permlane32_swap_b32_e32 v72, v74
	v_permlane32_swap_b32_e32 v73, v75
	v_permlane32_swap_b32_e32 v76, v78
	v_permlane32_swap_b32_e32 v77, v79
	v_permlane32_swap_b32_e32 v80, v82
	v_permlane32_swap_b32_e32 v81, v83
	s_addk_i32 s8, 0xc000
	s_cmp_lg_u32 s28, 0
	s_cselect_b32 s0, s8, 0x8000
	v_add_u32_e32 v88, s0, v178
	ds_read_b64_tr_b16 v[84:85], v88 offset:0
	ds_read_b64_tr_b16 v[86:87], v88 offset:0x800
	ds_read_b64_tr_b16 v[92:93], v88 offset:0x1000
	ds_read_b64_tr_b16 v[94:95], v88 offset:0x1800
	ds_read_b64_tr_b16 v[96:97], v88 offset:0x2000
	ds_read_b64_tr_b16 v[98:99], v88 offset:0x2800
	ds_read_b64_tr_b16 v[100:101], v88 offset:0x3000
	ds_read_b64_tr_b16 v[102:103], v88 offset:0x3800
	s_waitcnt lgkmcnt(0)
	s_nop 0
	v_mfma_f32_32x32x16_bf16 v[2:17], v[68:71], v[84:87], v[2:17]
	ds_read_b64_tr_b16 v[84:85], v88 offset:0x200
	ds_read_b64_tr_b16 v[86:87], v88 offset:0xa00
	v_mfma_f32_32x32x16_bf16 v[2:17], v[72:75], v[92:95], v[2:17]
	ds_read_b64_tr_b16 v[92:93], v88 offset:0x1200
	ds_read_b64_tr_b16 v[94:95], v88 offset:0x1a00
	v_mfma_f32_32x32x16_bf16 v[2:17], v[76:79], v[96:99], v[2:17]
	ds_read_b64_tr_b16 v[96:97], v88 offset:0x2200
	ds_read_b64_tr_b16 v[98:99], v88 offset:0x2a00
	v_mfma_f32_32x32x16_bf16 v[2:17], v[80:83], v[100:103], v[2:17]
	ds_read_b64_tr_b16 v[100:101], v88 offset:0x3200
	ds_read_b64_tr_b16 v[102:103], v88 offset:0x3a00
	s_waitcnt lgkmcnt(0)
	v_mfma_f32_32x32x16_bf16 v[50:65], v[68:71], v[84:87], v[50:65]
	ds_read_b64_tr_b16 v[84:85], v88 offset:0x400
	ds_read_b64_tr_b16 v[86:87], v88 offset:0xc00
	v_mfma_f32_32x32x16_bf16 v[50:65], v[72:75], v[92:95], v[50:65]
	ds_read_b64_tr_b16 v[92:93], v88 offset:0x1400
	ds_read_b64_tr_b16 v[94:95], v88 offset:0x1c00
	v_mfma_f32_32x32x16_bf16 v[50:65], v[76:79], v[96:99], v[50:65]
	ds_read_b64_tr_b16 v[96:97], v88 offset:0x2400
	ds_read_b64_tr_b16 v[98:99], v88 offset:0x2c00
	v_mfma_f32_32x32x16_bf16 v[50:65], v[80:83], v[100:103], v[50:65]
	ds_read_b64_tr_b16 v[100:101], v88 offset:0x3400
	ds_read_b64_tr_b16 v[102:103], v88 offset:0x3c00
	s_waitcnt lgkmcnt(0)
	v_mfma_f32_32x32x16_bf16 v[34:49], v[68:71], v[84:87], v[34:49]
	ds_read_b64_tr_b16 v[84:85], v88 offset:0x600
	ds_read_b64_tr_b16 v[86:87], v88 offset:0xe00
	v_mfma_f32_32x32x16_bf16 v[34:49], v[72:75], v[92:95], v[34:49]
	ds_read_b64_tr_b16 v[92:93], v88 offset:0x1600
	ds_read_b64_tr_b16 v[94:95], v88 offset:0x1e00
	v_mfma_f32_32x32x16_bf16 v[34:49], v[76:79], v[96:99], v[34:49]
	ds_read_b64_tr_b16 v[96:97], v88 offset:0x2600
	ds_read_b64_tr_b16 v[98:99], v88 offset:0x2e00
	v_mfma_f32_32x32x16_bf16 v[34:49], v[80:83], v[100:103], v[34:49]
	ds_read_b64_tr_b16 v[100:101], v88 offset:0x3600
	ds_read_b64_tr_b16 v[102:103], v88 offset:0x3e00
	s_waitcnt lgkmcnt(0)
	v_mfma_f32_32x32x16_bf16 v[18:33], v[68:71], v[84:87], v[18:33]
	v_mfma_f32_32x32x16_bf16 v[18:33], v[72:75], v[92:95], v[18:33]
	v_mfma_f32_32x32x16_bf16 v[18:33], v[76:79], v[96:99], v[18:33]
	v_mfma_f32_32x32x16_bf16 v[18:33], v[80:83], v[100:103], v[18:33]
	s_and_saveexec_b64 s[0:1], s[38:39]
	s_cbranch_execz .LBB0_258
	v_add_f32_e32 v66, v66, v67
	v_fmac_f32_e32 v66, v0, v230
	ds_write_b32 v190, v66
	s_branch .LBB0_258
